# GLA scan step 2b regenerated: no v_mov shuffles, q/k words read 4 positions per group with next group prefetched
# speedup vs baseline: 1.0072x; 1.0072x over previous
.LBB0_3091:
	ds_read_b128 v[76:79], v203 offset:62464
	ds_read_b128 v[80:83], v203 offset:62480
	ds_read_b128 v[216:219], v203 offset:62496
	ds_read_b128 v[174:177], v203 offset:62512
	s_waitcnt lgkmcnt(3)
	v_fma_f32 v115, v76, v120, v134
	v_fma_f32 v117, v76, v154, v135
	v_fmac_f32_e32 v115, v77, v122
	v_fmac_f32_e32 v117, v77, v156
	v_fmac_f32_e32 v115, v78, v118
	v_fmac_f32_e32 v117, v78, v158
	v_fmac_f32_e32 v115, v79, v124
	v_fmac_f32_e32 v117, v79, v160
	ds_read_b128 v[76:79], v203 offset:62528
	s_waitcnt lgkmcnt(3)
	v_fmac_f32_e32 v115, v80, v121
	v_fmac_f32_e32 v117, v80, v155
	v_fmac_f32_e32 v115, v81, v123
	v_fmac_f32_e32 v117, v81, v157
	v_fmac_f32_e32 v115, v82, v119
	v_fmac_f32_e32 v117, v82, v159
	v_fmac_f32_e32 v115, v83, v125
	v_fmac_f32_e32 v117, v83, v161
	ds_read_b128 v[80:83], v203 offset:62544
	s_waitcnt lgkmcnt(3)
	v_fmac_f32_e32 v115, v216, v126
	v_fmac_f32_e32 v117, v216, v146
	v_fmac_f32_e32 v115, v217, v128
	v_fmac_f32_e32 v117, v217, v148
	v_fmac_f32_e32 v115, v218, v130
	v_fmac_f32_e32 v117, v218, v150
	v_fmac_f32_e32 v115, v219, v132
	v_fmac_f32_e32 v117, v219, v152
	ds_read_b128 v[216:219], v203 offset:62560
	s_waitcnt lgkmcnt(3)
	v_fmac_f32_e32 v115, v174, v127
	v_fmac_f32_e32 v117, v174, v147
	v_fmac_f32_e32 v115, v175, v129
	v_fmac_f32_e32 v117, v175, v149
	v_fmac_f32_e32 v115, v176, v131
	v_fmac_f32_e32 v117, v176, v151
	v_fmac_f32_e32 v115, v177, v133
	v_fmac_f32_e32 v117, v177, v153
	ds_read_b128 v[174:177], v203 offset:62576
	v_mul_f32_e64 v178, |v115|, s86
	v_mul_f32_e64 v179, |v117|, s86
	v_exp_f32_e32 v178, v178
	v_exp_f32_e32 v179, v179
	v_max_f32_e64 v115, -v115, 0
	v_add_f32_e32 v178, 1.0, v178
	v_add_f32_e32 v179, 1.0, v179
	v_max_f32_e64 v117, -v117, 0
	v_log_f32_e32 v178, v178
	v_log_f32_e32 v179, v179
	s_nop 0
	v_fmac_f32_e32 v115, 0x3f317217, v178
	v_fmac_f32_e32 v117, 0x3f317217, v179
	v_mul_f32_e32 v115, 0xbdb8aa3b, v115
	v_mul_f32_e32 v117, 0xbdb8aa3b, v117
	v_exp_f32_e32 v84, v115
	v_exp_f32_e32 v85, v117
	s_waitcnt lgkmcnt(3)
	v_fma_f32 v115, v76, v120, v134
	v_fma_f32 v117, v76, v154, v135
	v_fmac_f32_e32 v115, v77, v122
	v_fmac_f32_e32 v117, v77, v156
	v_mov_b32_e32 v220, v84
	v_mov_b32_e32 v221, v85
	v_fmac_f32_e32 v115, v78, v118
	v_fmac_f32_e32 v117, v78, v158
	v_fmac_f32_e32 v115, v79, v124
	v_fmac_f32_e32 v117, v79, v160
	ds_read_b128 v[76:79], v203 offset:62592
	s_waitcnt lgkmcnt(3)
	v_fmac_f32_e32 v115, v80, v121
	v_fmac_f32_e32 v117, v80, v155
	v_fmac_f32_e32 v115, v81, v123
	v_fmac_f32_e32 v117, v81, v157
	v_fmac_f32_e32 v115, v82, v119
	v_fmac_f32_e32 v117, v82, v159
	v_fmac_f32_e32 v115, v83, v125
	v_fmac_f32_e32 v117, v83, v161
	ds_read_b128 v[80:83], v203 offset:62608
	s_waitcnt lgkmcnt(3)
	v_fmac_f32_e32 v115, v216, v126
	v_fmac_f32_e32 v117, v216, v146
	v_fmac_f32_e32 v115, v217, v128
	v_fmac_f32_e32 v117, v217, v148
	v_fmac_f32_e32 v115, v218, v130
	v_fmac_f32_e32 v117, v218, v150
	v_fmac_f32_e32 v115, v219, v132
	v_fmac_f32_e32 v117, v219, v152
	ds_read_b128 v[216:219], v203 offset:62624
	s_waitcnt lgkmcnt(3)
	v_fmac_f32_e32 v115, v174, v127
	v_fmac_f32_e32 v117, v174, v147
	v_fmac_f32_e32 v115, v175, v129
	v_fmac_f32_e32 v117, v175, v149
	v_fmac_f32_e32 v115, v176, v131
	v_fmac_f32_e32 v117, v176, v151
	v_fmac_f32_e32 v115, v177, v133
	v_fmac_f32_e32 v117, v177, v153
	ds_read_b128 v[174:177], v203 offset:62640
	v_mul_f32_e64 v178, |v115|, s86
	v_mul_f32_e64 v179, |v117|, s86
	v_exp_f32_e32 v178, v178
	v_exp_f32_e32 v179, v179
	v_max_f32_e64 v115, -v115, 0
	v_add_f32_e32 v178, 1.0, v178
	v_add_f32_e32 v179, 1.0, v179
	v_max_f32_e64 v117, -v117, 0
	v_log_f32_e32 v178, v178
	v_log_f32_e32 v179, v179
	s_nop 0
	v_fmac_f32_e32 v115, 0x3f317217, v178
	v_fmac_f32_e32 v117, 0x3f317217, v179
	v_mul_f32_e32 v115, 0xbdb8aa3b, v115
	v_mul_f32_e32 v117, 0xbdb8aa3b, v117
	v_exp_f32_e32 v86, v115
	v_exp_f32_e32 v87, v117
	s_waitcnt lgkmcnt(3)
	v_fma_f32 v115, v76, v120, v134
	v_fma_f32 v117, v76, v154, v135
	v_fmac_f32_e32 v115, v77, v122
	v_fmac_f32_e32 v117, v77, v156
	v_pk_mul_f32 v[220:221], v[220:221], v[86:87]
	v_fmac_f32_e32 v115, v78, v118
	v_fmac_f32_e32 v117, v78, v158
	v_fmac_f32_e32 v115, v79, v124
	v_fmac_f32_e32 v117, v79, v160
	ds_read_b128 v[76:79], v203 offset:62656
	s_waitcnt lgkmcnt(3)
	v_fmac_f32_e32 v115, v80, v121
	v_fmac_f32_e32 v117, v80, v155
	v_fmac_f32_e32 v115, v81, v123
	v_fmac_f32_e32 v117, v81, v157
	v_fmac_f32_e32 v115, v82, v119
	v_fmac_f32_e32 v117, v82, v159
	v_fmac_f32_e32 v115, v83, v125
	v_fmac_f32_e32 v117, v83, v161
	ds_read_b128 v[80:83], v203 offset:62672
	s_waitcnt lgkmcnt(3)
	v_fmac_f32_e32 v115, v216, v126
	v_fmac_f32_e32 v117, v216, v146
	v_fmac_f32_e32 v115, v217, v128
	v_fmac_f32_e32 v117, v217, v148
	v_fmac_f32_e32 v115, v218, v130
	v_fmac_f32_e32 v117, v218, v150
	v_fmac_f32_e32 v115, v219, v132
	v_fmac_f32_e32 v117, v219, v152
	ds_read_b128 v[216:219], v203 offset:62688
	s_waitcnt lgkmcnt(3)
	v_fmac_f32_e32 v115, v174, v127
	v_fmac_f32_e32 v117, v174, v147
	v_fmac_f32_e32 v115, v175, v129
	v_fmac_f32_e32 v117, v175, v149
	v_fmac_f32_e32 v115, v176, v131
	v_fmac_f32_e32 v117, v176, v151
	v_fmac_f32_e32 v115, v177, v133
	v_fmac_f32_e32 v117, v177, v153
	ds_read_b128 v[174:177], v203 offset:62704
	v_mul_f32_e64 v178, |v115|, s86
	v_mul_f32_e64 v179, |v117|, s86
	v_exp_f32_e32 v178, v178
	v_exp_f32_e32 v179, v179
	v_max_f32_e64 v115, -v115, 0
	v_add_f32_e32 v178, 1.0, v178
	v_add_f32_e32 v179, 1.0, v179
	v_max_f32_e64 v117, -v117, 0
	v_log_f32_e32 v178, v178
	v_log_f32_e32 v179, v179
	s_nop 0
	v_fmac_f32_e32 v115, 0x3f317217, v178
	v_fmac_f32_e32 v117, 0x3f317217, v179
	v_mul_f32_e32 v115, 0xbdb8aa3b, v115
	v_mul_f32_e32 v117, 0xbdb8aa3b, v117
	v_exp_f32_e32 v88, v115
	v_exp_f32_e32 v89, v117
	s_waitcnt lgkmcnt(3)
	v_fma_f32 v115, v76, v120, v134
	v_fma_f32 v117, v76, v154, v135
	v_fmac_f32_e32 v115, v77, v122
	v_fmac_f32_e32 v117, v77, v156
	v_pk_mul_f32 v[220:221], v[220:221], v[88:89]
	v_fmac_f32_e32 v115, v78, v118
	v_fmac_f32_e32 v117, v78, v158
	v_fmac_f32_e32 v115, v79, v124
	v_fmac_f32_e32 v117, v79, v160
	ds_read_b128 v[76:79], v203 offset:62720
	s_waitcnt lgkmcnt(3)
	v_fmac_f32_e32 v115, v80, v121
	v_fmac_f32_e32 v117, v80, v155
	v_fmac_f32_e32 v115, v81, v123
	v_fmac_f32_e32 v117, v81, v157
	v_fmac_f32_e32 v115, v82, v119
	v_fmac_f32_e32 v117, v82, v159
	v_fmac_f32_e32 v115, v83, v125
	v_fmac_f32_e32 v117, v83, v161
	ds_read_b128 v[80:83], v203 offset:62736
	s_waitcnt lgkmcnt(3)
	v_fmac_f32_e32 v115, v216, v126
	v_fmac_f32_e32 v117, v216, v146
	v_fmac_f32_e32 v115, v217, v128
	v_fmac_f32_e32 v117, v217, v148
	v_fmac_f32_e32 v115, v218, v130
	v_fmac_f32_e32 v117, v218, v150
	v_fmac_f32_e32 v115, v219, v132
	v_fmac_f32_e32 v117, v219, v152
	ds_read_b128 v[216:219], v203 offset:62752
	s_waitcnt lgkmcnt(3)
	v_fmac_f32_e32 v115, v174, v127
	v_fmac_f32_e32 v117, v174, v147
	v_fmac_f32_e32 v115, v175, v129
	v_fmac_f32_e32 v117, v175, v149
	v_fmac_f32_e32 v115, v176, v131
	v_fmac_f32_e32 v117, v176, v151
	v_fmac_f32_e32 v115, v177, v133
	v_fmac_f32_e32 v117, v177, v153
	ds_read_b128 v[174:177], v203 offset:62768
	v_mul_f32_e64 v178, |v115|, s86
	v_mul_f32_e64 v179, |v117|, s86
	v_exp_f32_e32 v178, v178
	v_exp_f32_e32 v179, v179
	v_max_f32_e64 v115, -v115, 0
	v_add_f32_e32 v178, 1.0, v178
	v_add_f32_e32 v179, 1.0, v179
	v_max_f32_e64 v117, -v117, 0
	v_log_f32_e32 v178, v178
	v_log_f32_e32 v179, v179
	s_nop 0
	v_fmac_f32_e32 v115, 0x3f317217, v178
	v_fmac_f32_e32 v117, 0x3f317217, v179
	v_mul_f32_e32 v115, 0xbdb8aa3b, v115
	v_mul_f32_e32 v117, 0xbdb8aa3b, v117
	v_exp_f32_e32 v90, v115
	v_exp_f32_e32 v91, v117
	s_waitcnt lgkmcnt(3)
	v_fma_f32 v115, v76, v120, v134
	v_fma_f32 v117, v76, v154, v135
	v_fmac_f32_e32 v115, v77, v122
	v_fmac_f32_e32 v117, v77, v156
	v_pk_mul_f32 v[220:221], v[220:221], v[90:91]
	v_fmac_f32_e32 v115, v78, v118
	v_fmac_f32_e32 v117, v78, v158
	v_fmac_f32_e32 v115, v79, v124
	v_fmac_f32_e32 v117, v79, v160
	ds_read_b128 v[76:79], v203 offset:62784
	s_waitcnt lgkmcnt(3)
	v_fmac_f32_e32 v115, v80, v121
	v_fmac_f32_e32 v117, v80, v155
	v_fmac_f32_e32 v115, v81, v123
	v_fmac_f32_e32 v117, v81, v157
	v_fmac_f32_e32 v115, v82, v119
	v_fmac_f32_e32 v117, v82, v159
	v_fmac_f32_e32 v115, v83, v125
	v_fmac_f32_e32 v117, v83, v161
	ds_read_b128 v[80:83], v203 offset:62800
	s_waitcnt lgkmcnt(3)
	v_fmac_f32_e32 v115, v216, v126
	v_fmac_f32_e32 v117, v216, v146
	v_fmac_f32_e32 v115, v217, v128
	v_fmac_f32_e32 v117, v217, v148
	v_fmac_f32_e32 v115, v218, v130
	v_fmac_f32_e32 v117, v218, v150
	v_fmac_f32_e32 v115, v219, v132
	v_fmac_f32_e32 v117, v219, v152
	ds_read_b128 v[216:219], v203 offset:62816
	s_waitcnt lgkmcnt(3)
	v_fmac_f32_e32 v115, v174, v127
	v_fmac_f32_e32 v117, v174, v147
	v_fmac_f32_e32 v115, v175, v129
	v_fmac_f32_e32 v117, v175, v149
	v_fmac_f32_e32 v115, v176, v131
	v_fmac_f32_e32 v117, v176, v151
	v_fmac_f32_e32 v115, v177, v133
	v_fmac_f32_e32 v117, v177, v153
	ds_read_b128 v[174:177], v203 offset:62832
	v_mul_f32_e64 v178, |v115|, s86
	v_mul_f32_e64 v179, |v117|, s86
	v_exp_f32_e32 v178, v178
	v_exp_f32_e32 v179, v179
	v_max_f32_e64 v115, -v115, 0
	v_add_f32_e32 v178, 1.0, v178
	v_add_f32_e32 v179, 1.0, v179
	v_max_f32_e64 v117, -v117, 0
	v_log_f32_e32 v178, v178
	v_log_f32_e32 v179, v179
	s_nop 0
	v_fmac_f32_e32 v115, 0x3f317217, v178
	v_fmac_f32_e32 v117, 0x3f317217, v179
	v_mul_f32_e32 v115, 0xbdb8aa3b, v115
	v_mul_f32_e32 v117, 0xbdb8aa3b, v117
	v_exp_f32_e32 v92, v115
	v_exp_f32_e32 v93, v117
	s_waitcnt lgkmcnt(3)
	v_fma_f32 v115, v76, v120, v134
	v_fma_f32 v117, v76, v154, v135
	v_fmac_f32_e32 v115, v77, v122
	v_fmac_f32_e32 v117, v77, v156
	v_pk_mul_f32 v[220:221], v[220:221], v[92:93]
	v_fmac_f32_e32 v115, v78, v118
	v_fmac_f32_e32 v117, v78, v158
	v_fmac_f32_e32 v115, v79, v124
	v_fmac_f32_e32 v117, v79, v160
	ds_read_b128 v[76:79], v203 offset:62848
	s_waitcnt lgkmcnt(3)
	v_fmac_f32_e32 v115, v80, v121
	v_fmac_f32_e32 v117, v80, v155
	v_fmac_f32_e32 v115, v81, v123
	v_fmac_f32_e32 v117, v81, v157
	v_fmac_f32_e32 v115, v82, v119
	v_fmac_f32_e32 v117, v82, v159
	v_fmac_f32_e32 v115, v83, v125
	v_fmac_f32_e32 v117, v83, v161
	ds_read_b128 v[80:83], v203 offset:62864
	s_waitcnt lgkmcnt(3)
	v_fmac_f32_e32 v115, v216, v126
	v_fmac_f32_e32 v117, v216, v146
	v_fmac_f32_e32 v115, v217, v128
	v_fmac_f32_e32 v117, v217, v148
	v_fmac_f32_e32 v115, v218, v130
	v_fmac_f32_e32 v117, v218, v150
	v_fmac_f32_e32 v115, v219, v132
	v_fmac_f32_e32 v117, v219, v152
	ds_read_b128 v[216:219], v203 offset:62880
	s_waitcnt lgkmcnt(3)
	v_fmac_f32_e32 v115, v174, v127
	v_fmac_f32_e32 v117, v174, v147
	v_fmac_f32_e32 v115, v175, v129
	v_fmac_f32_e32 v117, v175, v149
	v_fmac_f32_e32 v115, v176, v131
	v_fmac_f32_e32 v117, v176, v151
	v_fmac_f32_e32 v115, v177, v133
	v_fmac_f32_e32 v117, v177, v153
	ds_read_b128 v[174:177], v203 offset:62896
	v_mul_f32_e64 v178, |v115|, s86
	v_mul_f32_e64 v179, |v117|, s86
	v_exp_f32_e32 v178, v178
	v_exp_f32_e32 v179, v179
	v_max_f32_e64 v115, -v115, 0
	v_add_f32_e32 v178, 1.0, v178
	v_add_f32_e32 v179, 1.0, v179
	v_max_f32_e64 v117, -v117, 0
	v_log_f32_e32 v178, v178
	v_log_f32_e32 v179, v179
	s_nop 0
	v_fmac_f32_e32 v115, 0x3f317217, v178
	v_fmac_f32_e32 v117, 0x3f317217, v179
	v_mul_f32_e32 v115, 0xbdb8aa3b, v115
	v_mul_f32_e32 v117, 0xbdb8aa3b, v117
	v_exp_f32_e32 v94, v115
	v_exp_f32_e32 v95, v117
	s_waitcnt lgkmcnt(3)
	v_fma_f32 v115, v76, v120, v134
	v_fma_f32 v117, v76, v154, v135
	v_fmac_f32_e32 v115, v77, v122
	v_fmac_f32_e32 v117, v77, v156
	v_pk_mul_f32 v[220:221], v[220:221], v[94:95]
	v_fmac_f32_e32 v115, v78, v118
	v_fmac_f32_e32 v117, v78, v158
	v_fmac_f32_e32 v115, v79, v124
	v_fmac_f32_e32 v117, v79, v160
	ds_read_b128 v[76:79], v203 offset:62912
	s_waitcnt lgkmcnt(3)
	v_fmac_f32_e32 v115, v80, v121
	v_fmac_f32_e32 v117, v80, v155
	v_fmac_f32_e32 v115, v81, v123
	v_fmac_f32_e32 v117, v81, v157
	v_fmac_f32_e32 v115, v82, v119
	v_fmac_f32_e32 v117, v82, v159
	v_fmac_f32_e32 v115, v83, v125
	v_fmac_f32_e32 v117, v83, v161
	ds_read_b128 v[80:83], v203 offset:62928
	s_waitcnt lgkmcnt(3)
	v_fmac_f32_e32 v115, v216, v126
	v_fmac_f32_e32 v117, v216, v146
	v_fmac_f32_e32 v115, v217, v128
	v_fmac_f32_e32 v117, v217, v148
	v_fmac_f32_e32 v115, v218, v130
	v_fmac_f32_e32 v117, v218, v150
	v_fmac_f32_e32 v115, v219, v132
	v_fmac_f32_e32 v117, v219, v152
	ds_read_b128 v[216:219], v203 offset:62944
	s_waitcnt lgkmcnt(3)
	v_fmac_f32_e32 v115, v174, v127
	v_fmac_f32_e32 v117, v174, v147
	v_fmac_f32_e32 v115, v175, v129
	v_fmac_f32_e32 v117, v175, v149
	v_fmac_f32_e32 v115, v176, v131
	v_fmac_f32_e32 v117, v176, v151
	v_fmac_f32_e32 v115, v177, v133
	v_fmac_f32_e32 v117, v177, v153
	ds_read_b128 v[174:177], v203 offset:62960
	v_mul_f32_e64 v178, |v115|, s86
	v_mul_f32_e64 v179, |v117|, s86
	v_exp_f32_e32 v178, v178
	v_exp_f32_e32 v179, v179
	v_max_f32_e64 v115, -v115, 0
	v_add_f32_e32 v178, 1.0, v178
	v_add_f32_e32 v179, 1.0, v179
	v_max_f32_e64 v117, -v117, 0
	v_log_f32_e32 v178, v178
	v_log_f32_e32 v179, v179
	s_nop 0
	v_fmac_f32_e32 v115, 0x3f317217, v178
	v_fmac_f32_e32 v117, 0x3f317217, v179
	v_mul_f32_e32 v115, 0xbdb8aa3b, v115
	v_mul_f32_e32 v117, 0xbdb8aa3b, v117
	v_exp_f32_e32 v96, v115
	v_exp_f32_e32 v97, v117
	s_waitcnt lgkmcnt(3)
	v_fma_f32 v115, v76, v120, v134
	v_fma_f32 v117, v76, v154, v135
	v_fmac_f32_e32 v115, v77, v122
	v_fmac_f32_e32 v117, v77, v156
	v_pk_mul_f32 v[220:221], v[220:221], v[96:97]
	v_fmac_f32_e32 v115, v78, v118
	v_fmac_f32_e32 v117, v78, v158
	v_fmac_f32_e32 v115, v79, v124
	v_fmac_f32_e32 v117, v79, v160
	ds_read_b128 v[76:79], v203 offset:62976
	s_waitcnt lgkmcnt(3)
	v_fmac_f32_e32 v115, v80, v121
	v_fmac_f32_e32 v117, v80, v155
	v_fmac_f32_e32 v115, v81, v123
	v_fmac_f32_e32 v117, v81, v157
	v_fmac_f32_e32 v115, v82, v119
	v_fmac_f32_e32 v117, v82, v159
	v_fmac_f32_e32 v115, v83, v125
	v_fmac_f32_e32 v117, v83, v161
	ds_read_b128 v[80:83], v203 offset:62992
	s_waitcnt lgkmcnt(3)
	v_fmac_f32_e32 v115, v216, v126
	v_fmac_f32_e32 v117, v216, v146
	v_fmac_f32_e32 v115, v217, v128
	v_fmac_f32_e32 v117, v217, v148
	v_fmac_f32_e32 v115, v218, v130
	v_fmac_f32_e32 v117, v218, v150
	v_fmac_f32_e32 v115, v219, v132
	v_fmac_f32_e32 v117, v219, v152
	ds_read_b128 v[216:219], v203 offset:63008
	s_waitcnt lgkmcnt(3)
	v_fmac_f32_e32 v115, v174, v127
	v_fmac_f32_e32 v117, v174, v147
	v_fmac_f32_e32 v115, v175, v129
	v_fmac_f32_e32 v117, v175, v149
	v_fmac_f32_e32 v115, v176, v131
	v_fmac_f32_e32 v117, v176, v151
	v_fmac_f32_e32 v115, v177, v133
	v_fmac_f32_e32 v117, v177, v153
	ds_read_b128 v[174:177], v203 offset:63024
	v_mul_f32_e64 v178, |v115|, s86
	v_mul_f32_e64 v179, |v117|, s86
	v_exp_f32_e32 v178, v178
	v_exp_f32_e32 v179, v179
	v_max_f32_e64 v115, -v115, 0
	v_add_f32_e32 v178, 1.0, v178
	v_add_f32_e32 v179, 1.0, v179
	v_max_f32_e64 v117, -v117, 0
	v_log_f32_e32 v178, v178
	v_log_f32_e32 v179, v179
	s_nop 0
	v_fmac_f32_e32 v115, 0x3f317217, v178
	v_fmac_f32_e32 v117, 0x3f317217, v179
	v_mul_f32_e32 v115, 0xbdb8aa3b, v115
	v_mul_f32_e32 v117, 0xbdb8aa3b, v117
	v_exp_f32_e32 v98, v115
	v_exp_f32_e32 v99, v117
	s_waitcnt lgkmcnt(3)
	v_fma_f32 v115, v76, v120, v134
	v_fma_f32 v117, v76, v154, v135
	v_fmac_f32_e32 v115, v77, v122
	v_fmac_f32_e32 v117, v77, v156
	v_pk_mul_f32 v[220:221], v[220:221], v[98:99]
	v_fmac_f32_e32 v115, v78, v118
	v_fmac_f32_e32 v117, v78, v158
	v_fmac_f32_e32 v115, v79, v124
	v_fmac_f32_e32 v117, v79, v160
	ds_read_b128 v[76:79], v203 offset:63040
	s_waitcnt lgkmcnt(3)
	v_fmac_f32_e32 v115, v80, v121
	v_fmac_f32_e32 v117, v80, v155
	v_fmac_f32_e32 v115, v81, v123
	v_fmac_f32_e32 v117, v81, v157
	v_fmac_f32_e32 v115, v82, v119
	v_fmac_f32_e32 v117, v82, v159
	v_fmac_f32_e32 v115, v83, v125
	v_fmac_f32_e32 v117, v83, v161
	ds_read_b128 v[80:83], v203 offset:63056
	s_waitcnt lgkmcnt(3)
	v_fmac_f32_e32 v115, v216, v126
	v_fmac_f32_e32 v117, v216, v146
	v_fmac_f32_e32 v115, v217, v128
	v_fmac_f32_e32 v117, v217, v148
	v_fmac_f32_e32 v115, v218, v130
	v_fmac_f32_e32 v117, v218, v150
	v_fmac_f32_e32 v115, v219, v132
	v_fmac_f32_e32 v117, v219, v152
	ds_read_b128 v[216:219], v203 offset:63072
	s_waitcnt lgkmcnt(3)
	v_fmac_f32_e32 v115, v174, v127
	v_fmac_f32_e32 v117, v174, v147
	v_fmac_f32_e32 v115, v175, v129
	v_fmac_f32_e32 v117, v175, v149
	v_fmac_f32_e32 v115, v176, v131
	v_fmac_f32_e32 v117, v176, v151
	v_fmac_f32_e32 v115, v177, v133
	v_fmac_f32_e32 v117, v177, v153
	ds_read_b128 v[174:177], v203 offset:63088
	v_mul_f32_e64 v178, |v115|, s86
	v_mul_f32_e64 v179, |v117|, s86
	v_exp_f32_e32 v178, v178
	v_exp_f32_e32 v179, v179
	v_max_f32_e64 v115, -v115, 0
	v_add_f32_e32 v178, 1.0, v178
	v_add_f32_e32 v179, 1.0, v179
	v_max_f32_e64 v117, -v117, 0
	v_log_f32_e32 v178, v178
	v_log_f32_e32 v179, v179
	s_nop 0
	v_fmac_f32_e32 v115, 0x3f317217, v178
	v_fmac_f32_e32 v117, 0x3f317217, v179
	v_mul_f32_e32 v115, 0xbdb8aa3b, v115
	v_mul_f32_e32 v117, 0xbdb8aa3b, v117
	v_exp_f32_e32 v162, v115
	v_exp_f32_e32 v163, v117
	s_waitcnt lgkmcnt(3)
	v_fma_f32 v115, v76, v120, v134
	v_fma_f32 v117, v76, v154, v135
	v_fmac_f32_e32 v115, v77, v122
	v_fmac_f32_e32 v117, v77, v156
	v_pk_mul_f32 v[220:221], v[220:221], v[162:163]
	v_fmac_f32_e32 v115, v78, v118
	v_fmac_f32_e32 v117, v78, v158
	v_fmac_f32_e32 v115, v79, v124
	v_fmac_f32_e32 v117, v79, v160
	ds_read_b128 v[76:79], v203 offset:63104
	s_waitcnt lgkmcnt(3)
	v_fmac_f32_e32 v115, v80, v121
	v_fmac_f32_e32 v117, v80, v155
	v_fmac_f32_e32 v115, v81, v123
	v_fmac_f32_e32 v117, v81, v157
	v_fmac_f32_e32 v115, v82, v119
	v_fmac_f32_e32 v117, v82, v159
	v_fmac_f32_e32 v115, v83, v125
	v_fmac_f32_e32 v117, v83, v161
	ds_read_b128 v[80:83], v203 offset:63120
	s_waitcnt lgkmcnt(3)
	v_fmac_f32_e32 v115, v216, v126
	v_fmac_f32_e32 v117, v216, v146
	v_fmac_f32_e32 v115, v217, v128
	v_fmac_f32_e32 v117, v217, v148
	v_fmac_f32_e32 v115, v218, v130
	v_fmac_f32_e32 v117, v218, v150
	v_fmac_f32_e32 v115, v219, v132
	v_fmac_f32_e32 v117, v219, v152
	ds_read_b128 v[216:219], v203 offset:63136
	s_waitcnt lgkmcnt(3)
	v_fmac_f32_e32 v115, v174, v127
	v_fmac_f32_e32 v117, v174, v147
	v_fmac_f32_e32 v115, v175, v129
	v_fmac_f32_e32 v117, v175, v149
	v_fmac_f32_e32 v115, v176, v131
	v_fmac_f32_e32 v117, v176, v151
	v_fmac_f32_e32 v115, v177, v133
	v_fmac_f32_e32 v117, v177, v153
	ds_read_b128 v[174:177], v203 offset:63152
	v_mul_f32_e64 v178, |v115|, s86
	v_mul_f32_e64 v179, |v117|, s86
	v_exp_f32_e32 v178, v178
	v_exp_f32_e32 v179, v179
	v_max_f32_e64 v115, -v115, 0
	v_add_f32_e32 v178, 1.0, v178
	v_add_f32_e32 v179, 1.0, v179
	v_max_f32_e64 v117, -v117, 0
	v_log_f32_e32 v178, v178
	v_log_f32_e32 v179, v179
	s_nop 0
	v_fmac_f32_e32 v115, 0x3f317217, v178
	v_fmac_f32_e32 v117, 0x3f317217, v179
	v_mul_f32_e32 v115, 0xbdb8aa3b, v115
	v_mul_f32_e32 v117, 0xbdb8aa3b, v117
	v_exp_f32_e32 v164, v115
	v_exp_f32_e32 v165, v117
	s_waitcnt lgkmcnt(3)
	v_fma_f32 v115, v76, v120, v134
	v_fma_f32 v117, v76, v154, v135
	v_fmac_f32_e32 v115, v77, v122
	v_fmac_f32_e32 v117, v77, v156
	v_pk_mul_f32 v[220:221], v[220:221], v[164:165]
	v_fmac_f32_e32 v115, v78, v118
	v_fmac_f32_e32 v117, v78, v158
	v_fmac_f32_e32 v115, v79, v124
	v_fmac_f32_e32 v117, v79, v160
	ds_read_b128 v[76:79], v203 offset:63168
	s_waitcnt lgkmcnt(3)
	v_fmac_f32_e32 v115, v80, v121
	v_fmac_f32_e32 v117, v80, v155
	v_fmac_f32_e32 v115, v81, v123
	v_fmac_f32_e32 v117, v81, v157
	v_fmac_f32_e32 v115, v82, v119
	v_fmac_f32_e32 v117, v82, v159
	v_fmac_f32_e32 v115, v83, v125
	v_fmac_f32_e32 v117, v83, v161
	ds_read_b128 v[80:83], v203 offset:63184
	s_waitcnt lgkmcnt(3)
	v_fmac_f32_e32 v115, v216, v126
	v_fmac_f32_e32 v117, v216, v146
	v_fmac_f32_e32 v115, v217, v128
	v_fmac_f32_e32 v117, v217, v148
	v_fmac_f32_e32 v115, v218, v130
	v_fmac_f32_e32 v117, v218, v150
	v_fmac_f32_e32 v115, v219, v132
	v_fmac_f32_e32 v117, v219, v152
	ds_read_b128 v[216:219], v203 offset:63200
	s_waitcnt lgkmcnt(3)
	v_fmac_f32_e32 v115, v174, v127
	v_fmac_f32_e32 v117, v174, v147
	v_fmac_f32_e32 v115, v175, v129
	v_fmac_f32_e32 v117, v175, v149
	v_fmac_f32_e32 v115, v176, v131
	v_fmac_f32_e32 v117, v176, v151
	v_fmac_f32_e32 v115, v177, v133
	v_fmac_f32_e32 v117, v177, v153
	ds_read_b128 v[174:177], v203 offset:63216
	v_mul_f32_e64 v178, |v115|, s86
	v_mul_f32_e64 v179, |v117|, s86
	v_exp_f32_e32 v178, v178
	v_exp_f32_e32 v179, v179
	v_max_f32_e64 v115, -v115, 0
	v_add_f32_e32 v178, 1.0, v178
	v_add_f32_e32 v179, 1.0, v179
	v_max_f32_e64 v117, -v117, 0
	v_log_f32_e32 v178, v178
	v_log_f32_e32 v179, v179
	s_nop 0
	v_fmac_f32_e32 v115, 0x3f317217, v178
	v_fmac_f32_e32 v117, 0x3f317217, v179
	v_mul_f32_e32 v115, 0xbdb8aa3b, v115
	v_mul_f32_e32 v117, 0xbdb8aa3b, v117
	v_exp_f32_e32 v166, v115
	v_exp_f32_e32 v167, v117
	s_waitcnt lgkmcnt(3)
	v_fma_f32 v115, v76, v120, v134
	v_fma_f32 v117, v76, v154, v135
	v_fmac_f32_e32 v115, v77, v122
	v_fmac_f32_e32 v117, v77, v156
	v_pk_mul_f32 v[220:221], v[220:221], v[166:167]
	v_fmac_f32_e32 v115, v78, v118
	v_fmac_f32_e32 v117, v78, v158
	v_fmac_f32_e32 v115, v79, v124
	v_fmac_f32_e32 v117, v79, v160
	ds_read_b128 v[76:79], v203 offset:63232
	s_waitcnt lgkmcnt(3)
	v_fmac_f32_e32 v115, v80, v121
	v_fmac_f32_e32 v117, v80, v155
	v_fmac_f32_e32 v115, v81, v123
	v_fmac_f32_e32 v117, v81, v157
	v_fmac_f32_e32 v115, v82, v119
	v_fmac_f32_e32 v117, v82, v159
	v_fmac_f32_e32 v115, v83, v125
	v_fmac_f32_e32 v117, v83, v161
	ds_read_b128 v[80:83], v203 offset:63248
	s_waitcnt lgkmcnt(3)
	v_fmac_f32_e32 v115, v216, v126
	v_fmac_f32_e32 v117, v216, v146
	v_fmac_f32_e32 v115, v217, v128
	v_fmac_f32_e32 v117, v217, v148
	v_fmac_f32_e32 v115, v218, v130
	v_fmac_f32_e32 v117, v218, v150
	v_fmac_f32_e32 v115, v219, v132
	v_fmac_f32_e32 v117, v219, v152
	ds_read_b128 v[216:219], v203 offset:63264
	s_waitcnt lgkmcnt(3)
	v_fmac_f32_e32 v115, v174, v127
	v_fmac_f32_e32 v117, v174, v147
	v_fmac_f32_e32 v115, v175, v129
	v_fmac_f32_e32 v117, v175, v149
	v_fmac_f32_e32 v115, v176, v131
	v_fmac_f32_e32 v117, v176, v151
	v_fmac_f32_e32 v115, v177, v133
	v_fmac_f32_e32 v117, v177, v153
	ds_read_b128 v[174:177], v203 offset:63280
	v_mul_f32_e64 v178, |v115|, s86
	v_mul_f32_e64 v179, |v117|, s86
	v_exp_f32_e32 v178, v178
	v_exp_f32_e32 v179, v179
	v_max_f32_e64 v115, -v115, 0
	v_add_f32_e32 v178, 1.0, v178
	v_add_f32_e32 v179, 1.0, v179
	v_max_f32_e64 v117, -v117, 0
	v_log_f32_e32 v178, v178
	v_log_f32_e32 v179, v179
	s_nop 0
	v_fmac_f32_e32 v115, 0x3f317217, v178
	v_fmac_f32_e32 v117, 0x3f317217, v179
	v_mul_f32_e32 v115, 0xbdb8aa3b, v115
	v_mul_f32_e32 v117, 0xbdb8aa3b, v117
	v_exp_f32_e32 v168, v115
	v_exp_f32_e32 v169, v117
	s_waitcnt lgkmcnt(3)
	v_fma_f32 v115, v76, v120, v134
	v_fma_f32 v117, v76, v154, v135
	v_fmac_f32_e32 v115, v77, v122
	v_fmac_f32_e32 v117, v77, v156
	v_pk_mul_f32 v[220:221], v[220:221], v[168:169]
	v_fmac_f32_e32 v115, v78, v118
	v_fmac_f32_e32 v117, v78, v158
	v_fmac_f32_e32 v115, v79, v124
	v_fmac_f32_e32 v117, v79, v160
	ds_read_b128 v[76:79], v203 offset:63296
	s_waitcnt lgkmcnt(3)
	v_fmac_f32_e32 v115, v80, v121
	v_fmac_f32_e32 v117, v80, v155
	v_fmac_f32_e32 v115, v81, v123
	v_fmac_f32_e32 v117, v81, v157
	v_fmac_f32_e32 v115, v82, v119
	v_fmac_f32_e32 v117, v82, v159
	v_fmac_f32_e32 v115, v83, v125
	v_fmac_f32_e32 v117, v83, v161
	ds_read_b128 v[80:83], v203 offset:63312
	s_waitcnt lgkmcnt(3)
	v_fmac_f32_e32 v115, v216, v126
	v_fmac_f32_e32 v117, v216, v146
	v_fmac_f32_e32 v115, v217, v128
	v_fmac_f32_e32 v117, v217, v148
	v_fmac_f32_e32 v115, v218, v130
	v_fmac_f32_e32 v117, v218, v150
	v_fmac_f32_e32 v115, v219, v132
	v_fmac_f32_e32 v117, v219, v152
	ds_read_b128 v[216:219], v203 offset:63328
	s_waitcnt lgkmcnt(3)
	v_fmac_f32_e32 v115, v174, v127
	v_fmac_f32_e32 v117, v174, v147
	v_fmac_f32_e32 v115, v175, v129
	v_fmac_f32_e32 v117, v175, v149
	v_fmac_f32_e32 v115, v176, v131
	v_fmac_f32_e32 v117, v176, v151
	v_fmac_f32_e32 v115, v177, v133
	v_fmac_f32_e32 v117, v177, v153
	ds_read_b128 v[174:177], v203 offset:63344
	v_mul_f32_e64 v178, |v115|, s86
	v_mul_f32_e64 v179, |v117|, s86
	v_exp_f32_e32 v178, v178
	v_exp_f32_e32 v179, v179
	v_max_f32_e64 v115, -v115, 0
	v_add_f32_e32 v178, 1.0, v178
	v_add_f32_e32 v179, 1.0, v179
	v_max_f32_e64 v117, -v117, 0
	v_log_f32_e32 v178, v178
	v_log_f32_e32 v179, v179
	s_nop 0
	v_fmac_f32_e32 v115, 0x3f317217, v178
	v_fmac_f32_e32 v117, 0x3f317217, v179
	v_mul_f32_e32 v115, 0xbdb8aa3b, v115
	v_mul_f32_e32 v117, 0xbdb8aa3b, v117
	v_exp_f32_e32 v170, v115
	v_exp_f32_e32 v171, v117
	s_waitcnt lgkmcnt(3)
	v_fma_f32 v115, v76, v120, v134
	v_fma_f32 v117, v76, v154, v135
	v_fmac_f32_e32 v115, v77, v122
	v_fmac_f32_e32 v117, v77, v156
	v_pk_mul_f32 v[220:221], v[220:221], v[170:171]
	v_fmac_f32_e32 v115, v78, v118
	v_fmac_f32_e32 v117, v78, v158
	v_fmac_f32_e32 v115, v79, v124
	v_fmac_f32_e32 v117, v79, v160
	ds_read_b128 v[76:79], v203 offset:63360
	s_waitcnt lgkmcnt(3)
	v_fmac_f32_e32 v115, v80, v121
	v_fmac_f32_e32 v117, v80, v155
	v_fmac_f32_e32 v115, v81, v123
	v_fmac_f32_e32 v117, v81, v157
	v_fmac_f32_e32 v115, v82, v119
	v_fmac_f32_e32 v117, v82, v159
	v_fmac_f32_e32 v115, v83, v125
	v_fmac_f32_e32 v117, v83, v161
	ds_read_b128 v[80:83], v203 offset:63376
	s_waitcnt lgkmcnt(3)
	v_fmac_f32_e32 v115, v216, v126
	v_fmac_f32_e32 v117, v216, v146
	v_fmac_f32_e32 v115, v217, v128
	v_fmac_f32_e32 v117, v217, v148
	v_fmac_f32_e32 v115, v218, v130
	v_fmac_f32_e32 v117, v218, v150
	v_fmac_f32_e32 v115, v219, v132
	v_fmac_f32_e32 v117, v219, v152
	ds_read_b128 v[216:219], v203 offset:63392
	s_waitcnt lgkmcnt(3)
	v_fmac_f32_e32 v115, v174, v127
	v_fmac_f32_e32 v117, v174, v147
	v_fmac_f32_e32 v115, v175, v129
	v_fmac_f32_e32 v117, v175, v149
	v_fmac_f32_e32 v115, v176, v131
	v_fmac_f32_e32 v117, v176, v151
	v_fmac_f32_e32 v115, v177, v133
	v_fmac_f32_e32 v117, v177, v153
	ds_read_b128 v[174:177], v203 offset:63408
	v_mul_f32_e64 v178, |v115|, s86
	v_mul_f32_e64 v179, |v117|, s86
	v_exp_f32_e32 v178, v178
	v_exp_f32_e32 v179, v179
	v_max_f32_e64 v115, -v115, 0
	v_add_f32_e32 v178, 1.0, v178
	v_add_f32_e32 v179, 1.0, v179
	v_max_f32_e64 v117, -v117, 0
	v_log_f32_e32 v178, v178
	v_log_f32_e32 v179, v179
	s_nop 0
	v_fmac_f32_e32 v115, 0x3f317217, v178
	v_fmac_f32_e32 v117, 0x3f317217, v179
	v_mul_f32_e32 v115, 0xbdb8aa3b, v115
	v_mul_f32_e32 v117, 0xbdb8aa3b, v117
	v_exp_f32_e32 v172, v115
	v_exp_f32_e32 v173, v117
	s_waitcnt lgkmcnt(3)
	v_fma_f32 v115, v76, v120, v134
	v_fma_f32 v117, v76, v154, v135
	v_fmac_f32_e32 v115, v77, v122
	v_fmac_f32_e32 v117, v77, v156
	v_pk_mul_f32 v[220:221], v[220:221], v[172:173]
	v_fmac_f32_e32 v115, v78, v118
	v_fmac_f32_e32 v117, v78, v158
	v_fmac_f32_e32 v115, v79, v124
	v_fmac_f32_e32 v117, v79, v160
	ds_read_b128 v[76:79], v203 offset:63424
	s_waitcnt lgkmcnt(3)
	v_fmac_f32_e32 v115, v80, v121
	v_fmac_f32_e32 v117, v80, v155
	v_fmac_f32_e32 v115, v81, v123
	v_fmac_f32_e32 v117, v81, v157
	v_fmac_f32_e32 v115, v82, v119
	v_fmac_f32_e32 v117, v82, v159
	v_fmac_f32_e32 v115, v83, v125
	v_fmac_f32_e32 v117, v83, v161
	ds_read_b128 v[80:83], v203 offset:63440
	s_waitcnt lgkmcnt(3)
	v_fmac_f32_e32 v115, v216, v126
	v_fmac_f32_e32 v117, v216, v146
	v_fmac_f32_e32 v115, v217, v128
	v_fmac_f32_e32 v117, v217, v148
	v_fmac_f32_e32 v115, v218, v130
	v_fmac_f32_e32 v117, v218, v150
	v_fmac_f32_e32 v115, v219, v132
	v_fmac_f32_e32 v117, v219, v152
	ds_read_b128 v[216:219], v203 offset:63456
	s_waitcnt lgkmcnt(3)
	v_fmac_f32_e32 v115, v174, v127
	v_fmac_f32_e32 v117, v174, v147
	v_fmac_f32_e32 v115, v175, v129
	v_fmac_f32_e32 v117, v175, v149
	v_fmac_f32_e32 v115, v176, v131
	v_fmac_f32_e32 v117, v176, v151
	v_fmac_f32_e32 v115, v177, v133
	v_fmac_f32_e32 v117, v177, v153
	v_mul_f32_e64 v178, |v115|, s86
	v_mul_f32_e64 v179, |v117|, s86
	v_exp_f32_e32 v178, v178
	v_exp_f32_e32 v179, v179
	v_max_f32_e64 v115, -v115, 0
	v_add_f32_e32 v178, 1.0, v178
	v_add_f32_e32 v179, 1.0, v179
	v_max_f32_e64 v117, -v117, 0
	v_log_f32_e32 v178, v178
	v_log_f32_e32 v179, v179
	s_nop 0
	v_fmac_f32_e32 v115, 0x3f317217, v178
	v_fmac_f32_e32 v117, 0x3f317217, v179
	v_mul_f32_e32 v115, 0xbdb8aa3b, v115
	v_mul_f32_e32 v117, 0xbdb8aa3b, v117
	v_exp_f32_e32 v174, v115
	v_exp_f32_e32 v175, v117
	s_waitcnt lgkmcnt(2)
	v_fma_f32 v115, v76, v120, v134
	v_fma_f32 v117, v76, v154, v135
	v_fmac_f32_e32 v115, v77, v122
	v_fmac_f32_e32 v117, v77, v156
	v_pk_mul_f32 v[220:221], v[220:221], v[174:175]
	v_fmac_f32_e32 v115, v78, v118
	v_fmac_f32_e32 v117, v78, v158
	v_fmac_f32_e32 v115, v79, v124
	v_fmac_f32_e32 v117, v79, v160
	ds_read_b128 v[76:79], v203 offset:63472
	s_waitcnt lgkmcnt(2)
	v_fmac_f32_e32 v115, v80, v121
	v_fmac_f32_e32 v117, v80, v155
	v_fmac_f32_e32 v115, v81, v123
	v_fmac_f32_e32 v117, v81, v157
	v_fmac_f32_e32 v115, v82, v119
	v_fmac_f32_e32 v117, v82, v159
	v_fmac_f32_e32 v115, v83, v125
	v_fmac_f32_e32 v117, v83, v161
	s_waitcnt lgkmcnt(1)
	v_fmac_f32_e32 v115, v216, v126
	v_fmac_f32_e32 v117, v216, v146
	v_fmac_f32_e32 v115, v217, v128
	v_fmac_f32_e32 v117, v217, v148
	v_fmac_f32_e32 v115, v218, v130
	v_fmac_f32_e32 v117, v218, v150
	v_fmac_f32_e32 v115, v219, v132
	v_fmac_f32_e32 v117, v219, v152
	s_waitcnt lgkmcnt(0)
	v_fmac_f32_e32 v115, v76, v127
	v_fmac_f32_e32 v117, v76, v147
	v_fmac_f32_e32 v115, v77, v129
	v_fmac_f32_e32 v117, v77, v149
	v_fmac_f32_e32 v115, v78, v131
	v_fmac_f32_e32 v117, v78, v151
	v_fmac_f32_e32 v115, v79, v133
	v_fmac_f32_e32 v117, v79, v153
	v_mul_f32_e64 v178, |v115|, s86
	v_mul_f32_e64 v179, |v117|, s86
	v_exp_f32_e32 v178, v178
	v_exp_f32_e32 v179, v179
	v_max_f32_e64 v115, -v115, 0
	v_add_f32_e32 v178, 1.0, v178
	v_add_f32_e32 v179, 1.0, v179
	v_max_f32_e64 v117, -v117, 0
	v_log_f32_e32 v178, v178
	v_log_f32_e32 v179, v179
	s_nop 0
	v_fmac_f32_e32 v115, 0x3f317217, v178
	v_fmac_f32_e32 v117, 0x3f317217, v179
	v_mul_f32_e32 v115, 0xbdb8aa3b, v115
	v_mul_f32_e32 v117, 0xbdb8aa3b, v117
	v_exp_f32_e32 v176, v115
	v_exp_f32_e32 v177, v117
	s_nop 1
	v_pk_mul_f32 v[220:221], v[220:221], v[176:177]
	s_nop 0
	ds_write_b64 v192, v[220:221]
	s_waitcnt lgkmcnt(0)
	s_barrier
	ds_read2st64_b64 v[80:83], v191 offset1:1
	ds_read2st64_b64 v[76:79], v191 offset0:2 offset1:3
	s_waitcnt lgkmcnt(1)
	v_pk_mul_f32 v[178:179], v[80:81], v[82:83]
	s_waitcnt lgkmcnt(0)
	v_pk_mul_f32 v[178:179], v[178:179], v[76:77]
	s_nop 0
	v_pk_mul_f32 v[178:179], v[178:179], v[78:79]
	s_and_saveexec_b64 s[48:49], s[4:5]
	ds_write_b64 v197, v[178:179]
	s_or_b64 exec, exec, s[48:49]
	v_cndmask_b32_e64 v81, v81, 1.0, s[4:5]
	v_cndmask_b32_e64 v80, v80, 1.0, s[4:5]
	v_mul_f32_e32 v82, v80, v82
	v_mul_f32_e32 v83, v81, v83
	v_cndmask_b32_e64 v81, v81, v83, s[6:7]
	v_cndmask_b32_e64 v80, v80, v82, s[6:7]
	v_pk_mul_f32 v[76:77], v[80:81], v[76:77]
	v_add_u32_e32 v115, 0x4400, v200
	v_cndmask_b32_e64 v77, v81, v77, s[8:9]
	v_cndmask_b32_e64 v76, v80, v76, s[8:9]
	v_pk_mul_f32 v[78:79], v[76:77], v[78:79]
	v_cndmask_b32_e64 v77, v77, v79, s[10:11]
	v_cndmask_b32_e64 v76, v76, v78, s[10:11]
	v_add_u32_e32 v216, 0x0, v200
	v_add_u32_e32 v217, 0x4400, v200
	v_add_u32_e32 v117, 0x440, v200
	v_add_u32_e32 v115, 0x4840, v200
	ds_read2_b32 v[222:223], v216 offset1:68
	ds_read2_b32 v[226:227], v217 offset1:68
	ds_read2_b32 v[224:225], v216 offset0:136 offset1:204
	ds_read2_b32 v[228:229], v217 offset0:136 offset1:204
	ds_read2_b32 v[230:231], v117 offset1:68
	ds_read2_b32 v[234:235], v115 offset1:68
	ds_read2_b32 v[232:233], v117 offset0:136 offset1:204
	ds_read2_b32 v[236:237], v115 offset0:136 offset1:204
	s_waitcnt lgkmcnt(4)
	v_pk_mul_f32 v[76:77], v[76:77], v[84:85]
	v_lshlrev_b32_e32 v80, 16, v222
	v_and_b32_e32 v81, 0xffff0000, v222
	v_rcp_f32_e32 v78, v76
	v_rcp_f32_e32 v79, v77
	v_lshlrev_b32_e32 v82, 16, v226
	v_and_b32_e32 v83, 0xffff0000, v226
	v_pk_mul_f32 v[80:81], v[80:81], v[76:77]
	v_pk_mul_f32 v[220:221], v[178:179], v[78:79]
	v_pk_mul_f32 v[76:77], v[76:77], v[86:87]
	v_pk_mul_f32 v[218:219], v[82:83], v[78:79]
	v_pk_mul_f32 v[220:221], v[82:83], v[220:221]
	v_cvt_pk_bf16_f32 v222, v80, v81
	v_cvt_pk_bf16_f32 v226, v218, v219
	v_lshlrev_b32_e32 v80, 16, v223
	v_and_b32_e32 v81, 0xffff0000, v223
	v_rcp_f32_e32 v78, v76
	v_rcp_f32_e32 v79, v77
	v_lshlrev_b32_e32 v82, 16, v227
	v_and_b32_e32 v83, 0xffff0000, v227
	v_pk_mul_f32 v[80:81], v[80:81], v[76:77]
	v_pk_mul_f32 v[238:239], v[178:179], v[78:79]
	v_pk_mul_f32 v[218:219], v[82:83], v[78:79]
	v_pk_mul_f32 v[238:239], v[82:83], v[238:239]
	v_cvt_pk_bf16_f32 v223, v80, v81
	v_cvt_pk_bf16_f32 v227, v218, v219
	v_cvt_pk_bf16_f32 v80, v220, v238
	v_cvt_pk_bf16_f32 v81, v221, v239
	ds_write2_b32 v216, v222, v223 offset1:68
	ds_write2_b32 v217, v226, v227 offset1:68
	ds_write_b32 v193, v80 offset:34816
	ds_write_b32 v193, v81 offset:34960
	v_pk_mul_f32 v[76:77], v[76:77], v[88:89]
	v_lshlrev_b32_e32 v80, 16, v224
	v_and_b32_e32 v81, 0xffff0000, v224
	v_rcp_f32_e32 v78, v76
	v_rcp_f32_e32 v79, v77
	v_lshlrev_b32_e32 v82, 16, v228
	v_and_b32_e32 v83, 0xffff0000, v228
	v_pk_mul_f32 v[80:81], v[80:81], v[76:77]
	v_pk_mul_f32 v[220:221], v[178:179], v[78:79]
	v_pk_mul_f32 v[76:77], v[76:77], v[90:91]
	v_pk_mul_f32 v[218:219], v[82:83], v[78:79]
	v_pk_mul_f32 v[220:221], v[82:83], v[220:221]
	v_cvt_pk_bf16_f32 v224, v80, v81
	v_cvt_pk_bf16_f32 v228, v218, v219
	v_lshlrev_b32_e32 v80, 16, v225
	v_and_b32_e32 v81, 0xffff0000, v225
	v_rcp_f32_e32 v78, v76
	v_rcp_f32_e32 v79, v77
	v_lshlrev_b32_e32 v82, 16, v229
	v_and_b32_e32 v83, 0xffff0000, v229
	v_pk_mul_f32 v[80:81], v[80:81], v[76:77]
	v_pk_mul_f32 v[238:239], v[178:179], v[78:79]
	v_pk_mul_f32 v[218:219], v[82:83], v[78:79]
	v_pk_mul_f32 v[238:239], v[82:83], v[238:239]
	v_cvt_pk_bf16_f32 v225, v80, v81
	v_cvt_pk_bf16_f32 v229, v218, v219
	v_cvt_pk_bf16_f32 v80, v220, v238
	v_cvt_pk_bf16_f32 v81, v221, v239
	ds_write2_b32 v216, v224, v225 offset0:136 offset1:204
	ds_write2_b32 v217, v228, v229 offset0:136 offset1:204
	ds_write_b32 v193, v80 offset:34820
	ds_write_b32 v193, v81 offset:34964
	v_add_u32_e32 v216, 0x880, v200
	v_add_u32_e32 v217, 0x4c80, v200
	ds_read2_b32 v[222:223], v216 offset1:68
	ds_read2_b32 v[226:227], v217 offset1:68
	ds_read2_b32 v[224:225], v216 offset0:136 offset1:204
	ds_read2_b32 v[228:229], v217 offset0:136 offset1:204
	s_waitcnt lgkmcnt(12)
	v_pk_mul_f32 v[76:77], v[76:77], v[92:93]
	v_lshlrev_b32_e32 v80, 16, v230
	v_and_b32_e32 v81, 0xffff0000, v230
	v_rcp_f32_e32 v78, v76
	v_rcp_f32_e32 v79, v77
	v_lshlrev_b32_e32 v82, 16, v234
	v_and_b32_e32 v83, 0xffff0000, v234
	v_pk_mul_f32 v[80:81], v[80:81], v[76:77]
	v_pk_mul_f32 v[220:221], v[178:179], v[78:79]
	v_pk_mul_f32 v[76:77], v[76:77], v[94:95]
	v_pk_mul_f32 v[218:219], v[82:83], v[78:79]
	v_pk_mul_f32 v[220:221], v[82:83], v[220:221]
	v_cvt_pk_bf16_f32 v230, v80, v81
	v_cvt_pk_bf16_f32 v234, v218, v219
	v_lshlrev_b32_e32 v80, 16, v231
	v_and_b32_e32 v81, 0xffff0000, v231
	v_rcp_f32_e32 v78, v76
	v_rcp_f32_e32 v79, v77
	v_lshlrev_b32_e32 v82, 16, v235
	v_and_b32_e32 v83, 0xffff0000, v235
	v_pk_mul_f32 v[80:81], v[80:81], v[76:77]
	v_pk_mul_f32 v[238:239], v[178:179], v[78:79]
	v_pk_mul_f32 v[218:219], v[82:83], v[78:79]
	v_pk_mul_f32 v[238:239], v[82:83], v[238:239]
	v_cvt_pk_bf16_f32 v231, v80, v81
	v_cvt_pk_bf16_f32 v235, v218, v219
	v_cvt_pk_bf16_f32 v80, v220, v238
	v_cvt_pk_bf16_f32 v81, v221, v239
	ds_write2_b32 v117, v230, v231 offset1:68
	ds_write2_b32 v115, v234, v235 offset1:68
	ds_write_b32 v193, v80 offset:34824
	ds_write_b32 v193, v81 offset:34968
	v_pk_mul_f32 v[76:77], v[76:77], v[96:97]
	v_lshlrev_b32_e32 v80, 16, v232
	v_and_b32_e32 v81, 0xffff0000, v232
	v_rcp_f32_e32 v78, v76
	v_rcp_f32_e32 v79, v77
	v_lshlrev_b32_e32 v82, 16, v236
	v_and_b32_e32 v83, 0xffff0000, v236
	v_pk_mul_f32 v[80:81], v[80:81], v[76:77]
	v_pk_mul_f32 v[220:221], v[178:179], v[78:79]
	v_pk_mul_f32 v[76:77], v[76:77], v[98:99]
	v_pk_mul_f32 v[218:219], v[82:83], v[78:79]
	v_pk_mul_f32 v[220:221], v[82:83], v[220:221]
	v_cvt_pk_bf16_f32 v232, v80, v81
	v_cvt_pk_bf16_f32 v236, v218, v219
	v_lshlrev_b32_e32 v80, 16, v233
	v_and_b32_e32 v81, 0xffff0000, v233
	v_rcp_f32_e32 v78, v76
	v_rcp_f32_e32 v79, v77
	v_lshlrev_b32_e32 v82, 16, v237
	v_and_b32_e32 v83, 0xffff0000, v237
	v_pk_mul_f32 v[80:81], v[80:81], v[76:77]
	v_pk_mul_f32 v[238:239], v[178:179], v[78:79]
	v_pk_mul_f32 v[218:219], v[82:83], v[78:79]
	v_pk_mul_f32 v[238:239], v[82:83], v[238:239]
	v_cvt_pk_bf16_f32 v233, v80, v81
	v_cvt_pk_bf16_f32 v237, v218, v219
	v_cvt_pk_bf16_f32 v80, v220, v238
	v_cvt_pk_bf16_f32 v81, v221, v239
	ds_write2_b32 v117, v232, v233 offset0:136 offset1:204
	ds_write2_b32 v115, v236, v237 offset0:136 offset1:204
	ds_write_b32 v193, v80 offset:34828
	ds_write_b32 v193, v81 offset:34972
	v_add_u32_e32 v117, 0xcc0, v200
	v_add_u32_e32 v115, 0x50c0, v200
	ds_read2_b32 v[230:231], v117 offset1:68
	ds_read2_b32 v[234:235], v115 offset1:68
	ds_read2_b32 v[232:233], v117 offset0:136 offset1:204
	ds_read2_b32 v[236:237], v115 offset0:136 offset1:204
	s_waitcnt lgkmcnt(12)
	v_pk_mul_f32 v[76:77], v[76:77], v[162:163]
	v_lshlrev_b32_e32 v80, 16, v222
	v_and_b32_e32 v81, 0xffff0000, v222
	v_rcp_f32_e32 v78, v76
	v_rcp_f32_e32 v79, v77
	v_lshlrev_b32_e32 v82, 16, v226
	v_and_b32_e32 v83, 0xffff0000, v226
	v_pk_mul_f32 v[80:81], v[80:81], v[76:77]
	v_pk_mul_f32 v[220:221], v[178:179], v[78:79]
	v_pk_mul_f32 v[76:77], v[76:77], v[164:165]
	v_pk_mul_f32 v[218:219], v[82:83], v[78:79]
	v_pk_mul_f32 v[220:221], v[82:83], v[220:221]
	v_cvt_pk_bf16_f32 v222, v80, v81
	v_cvt_pk_bf16_f32 v226, v218, v219
	v_lshlrev_b32_e32 v80, 16, v223
	v_and_b32_e32 v81, 0xffff0000, v223
	v_rcp_f32_e32 v78, v76
	v_rcp_f32_e32 v79, v77
	v_lshlrev_b32_e32 v82, 16, v227
	v_and_b32_e32 v83, 0xffff0000, v227
	v_pk_mul_f32 v[80:81], v[80:81], v[76:77]
	v_pk_mul_f32 v[238:239], v[178:179], v[78:79]
	v_pk_mul_f32 v[218:219], v[82:83], v[78:79]
	v_pk_mul_f32 v[238:239], v[82:83], v[238:239]
	v_cvt_pk_bf16_f32 v223, v80, v81
	v_cvt_pk_bf16_f32 v227, v218, v219
	v_cvt_pk_bf16_f32 v80, v220, v238
	v_cvt_pk_bf16_f32 v81, v221, v239
	ds_write2_b32 v216, v222, v223 offset1:68
	ds_write2_b32 v217, v226, v227 offset1:68
	ds_write_b32 v193, v80 offset:34832
	ds_write_b32 v193, v81 offset:34976
	v_pk_mul_f32 v[76:77], v[76:77], v[166:167]
	v_lshlrev_b32_e32 v80, 16, v224
	v_and_b32_e32 v81, 0xffff0000, v224
	v_rcp_f32_e32 v78, v76
	v_rcp_f32_e32 v79, v77
	v_lshlrev_b32_e32 v82, 16, v228
	v_and_b32_e32 v83, 0xffff0000, v228
	v_pk_mul_f32 v[80:81], v[80:81], v[76:77]
	v_pk_mul_f32 v[220:221], v[178:179], v[78:79]
	v_pk_mul_f32 v[76:77], v[76:77], v[168:169]
	v_pk_mul_f32 v[218:219], v[82:83], v[78:79]
	v_pk_mul_f32 v[220:221], v[82:83], v[220:221]
	v_cvt_pk_bf16_f32 v224, v80, v81
	v_cvt_pk_bf16_f32 v228, v218, v219
	v_lshlrev_b32_e32 v80, 16, v225
	v_and_b32_e32 v81, 0xffff0000, v225
	v_rcp_f32_e32 v78, v76
	v_rcp_f32_e32 v79, v77
	v_lshlrev_b32_e32 v82, 16, v229
	v_and_b32_e32 v83, 0xffff0000, v229
	v_pk_mul_f32 v[80:81], v[80:81], v[76:77]
	v_pk_mul_f32 v[238:239], v[178:179], v[78:79]
	v_pk_mul_f32 v[218:219], v[82:83], v[78:79]
	v_pk_mul_f32 v[238:239], v[82:83], v[238:239]
	v_cvt_pk_bf16_f32 v225, v80, v81
	v_cvt_pk_bf16_f32 v229, v218, v219
	v_cvt_pk_bf16_f32 v80, v220, v238
	v_cvt_pk_bf16_f32 v81, v221, v239
	ds_write2_b32 v216, v224, v225 offset0:136 offset1:204
	ds_write2_b32 v217, v228, v229 offset0:136 offset1:204
	ds_write_b32 v193, v80 offset:34836
	ds_write_b32 v193, v81 offset:34980
	s_waitcnt lgkmcnt(8)
	v_pk_mul_f32 v[76:77], v[76:77], v[170:171]
	v_lshlrev_b32_e32 v80, 16, v230
	v_and_b32_e32 v81, 0xffff0000, v230
	v_rcp_f32_e32 v78, v76
	v_rcp_f32_e32 v79, v77
	v_lshlrev_b32_e32 v82, 16, v234
	v_and_b32_e32 v83, 0xffff0000, v234
	v_pk_mul_f32 v[80:81], v[80:81], v[76:77]
	v_pk_mul_f32 v[220:221], v[178:179], v[78:79]
	v_pk_mul_f32 v[76:77], v[76:77], v[172:173]
	v_pk_mul_f32 v[218:219], v[82:83], v[78:79]
	v_pk_mul_f32 v[220:221], v[82:83], v[220:221]
	v_cvt_pk_bf16_f32 v230, v80, v81
	v_cvt_pk_bf16_f32 v234, v218, v219
	v_lshlrev_b32_e32 v80, 16, v231
	v_and_b32_e32 v81, 0xffff0000, v231
	v_rcp_f32_e32 v78, v76
	v_rcp_f32_e32 v79, v77
	v_lshlrev_b32_e32 v82, 16, v235
	v_and_b32_e32 v83, 0xffff0000, v235
	v_pk_mul_f32 v[80:81], v[80:81], v[76:77]
	v_pk_mul_f32 v[238:239], v[178:179], v[78:79]
	v_pk_mul_f32 v[218:219], v[82:83], v[78:79]
	v_pk_mul_f32 v[238:239], v[82:83], v[238:239]
	v_cvt_pk_bf16_f32 v231, v80, v81
	v_cvt_pk_bf16_f32 v235, v218, v219
	v_cvt_pk_bf16_f32 v80, v220, v238
	v_cvt_pk_bf16_f32 v81, v221, v239
	ds_write2_b32 v117, v230, v231 offset1:68
	ds_write2_b32 v115, v234, v235 offset1:68
	ds_write_b32 v193, v80 offset:34840
	ds_write_b32 v193, v81 offset:34984
	v_pk_mul_f32 v[76:77], v[76:77], v[174:175]
	v_lshlrev_b32_e32 v80, 16, v232
	v_and_b32_e32 v81, 0xffff0000, v232
	v_rcp_f32_e32 v78, v76
	v_rcp_f32_e32 v79, v77
	v_lshlrev_b32_e32 v82, 16, v236
	v_and_b32_e32 v83, 0xffff0000, v236
	v_pk_mul_f32 v[80:81], v[80:81], v[76:77]
	v_pk_mul_f32 v[220:221], v[178:179], v[78:79]
	v_pk_mul_f32 v[76:77], v[76:77], v[176:177]
	v_pk_mul_f32 v[218:219], v[82:83], v[78:79]
	v_pk_mul_f32 v[220:221], v[82:83], v[220:221]
	v_cvt_pk_bf16_f32 v232, v80, v81
	v_cvt_pk_bf16_f32 v236, v218, v219
	v_lshlrev_b32_e32 v80, 16, v233
	v_and_b32_e32 v81, 0xffff0000, v233
	v_rcp_f32_e32 v78, v76
	v_rcp_f32_e32 v79, v77
	v_lshlrev_b32_e32 v82, 16, v237
	v_and_b32_e32 v83, 0xffff0000, v237
	v_pk_mul_f32 v[80:81], v[80:81], v[76:77]
	v_pk_mul_f32 v[238:239], v[178:179], v[78:79]
	v_pk_mul_f32 v[218:219], v[82:83], v[78:79]
	v_pk_mul_f32 v[238:239], v[82:83], v[238:239]
	v_cvt_pk_bf16_f32 v233, v80, v81
	v_cvt_pk_bf16_f32 v237, v218, v219
	v_cvt_pk_bf16_f32 v80, v220, v238
	v_cvt_pk_bf16_f32 v81, v221, v239
	ds_write2_b32 v117, v232, v233 offset0:136 offset1:204
	ds_write2_b32 v115, v236, v237 offset0:136 offset1:204
	ds_write_b32 v193, v80 offset:34844
	ds_write_b32 v193, v81 offset:34988
	s_cmp_lt_u32 s93, 4
	s_cselect_b64 s[48:49], -1, 0
	s_and_b64 vcc, exec, s[48:49]
	s_waitcnt lgkmcnt(0)
	s_barrier
	s_cbranch_vccnz .LBB0_3095
	ds_read_b128 v[76:79], v198
	v_add_u32_e32 v115, v196, v201
	ds_read_b128 v[80:83], v115 offset:17408
	ds_read_b128 v[84:87], v198 offset:64
	ds_read_b128 v[88:91], v115 offset:17472
	ds_read_b128 v[92:95], v115 offset:21760
	ds_read_b128 v[96:99], v115 offset:21824
	ds_read_b128 v[162:165], v115 offset:26112
	ds_read_b128 v[166:169], v115 offset:26176
	ds_read_b128 v[170:173], v115 offset:30464
	ds_read_b128 v[174:177], v115 offset:30528
	s_waitcnt lgkmcnt(8)
	v_mfma_f32_16x16x32_bf16 v[80:83], v[76:79], v[80:83], 0
	s_waitcnt lgkmcnt(5)
	v_mfma_f32_16x16x32_bf16 v[92:95], v[76:79], v[92:95], 0
	s_waitcnt lgkmcnt(3)
	v_mfma_f32_16x16x32_bf16 v[162:165], v[76:79], v[162:165], 0
	s_waitcnt lgkmcnt(1)
	v_mfma_f32_16x16x32_bf16 v[76:79], v[76:79], v[170:173], 0
	ds_read_b128 v[170:173], v198 offset:128
	ds_read_b128 v[216:219], v115 offset:17536
	v_mfma_f32_16x16x32_bf16 v[80:83], v[84:87], v[88:91], v[80:83]
	ds_read_b128 v[88:91], v198 offset:192
	ds_read_b128 v[220:223], v115 offset:17600
	s_waitcnt lgkmcnt(2)
	v_mfma_f32_16x16x32_bf16 v[80:83], v[170:173], v[216:219], v[80:83]
	ds_read_b128 v[216:219], v115 offset:21888
	ds_read_b128 v[224:227], v115 offset:21952
	ds_read_b128 v[228:231], v115 offset:26240
	ds_read_b128 v[232:235], v115 offset:26304
	s_waitcnt lgkmcnt(4)
	v_mfma_f32_16x16x32_bf16 v[80:83], v[88:91], v[220:223], v[80:83]
	ds_read_b128 v[220:223], v115 offset:30592
	ds_read_b128 v[236:239], v115 offset:30656
	v_mfma_f32_16x16x32_bf16 v[92:95], v[84:87], v[96:99], v[92:95]
	s_nop 4
	v_cvt_pk_bf16_f32 v80, v80, s0
	v_cndmask_b32_e64 v80, v80, 0, s[12:13]
	ds_write_b16 v204, v80 offset:62464
	v_cvt_pk_bf16_f32 v80, v81, s0
	v_cndmask_b32_e64 v80, v80, 0, s[14:15]
	s_waitcnt lgkmcnt(6)
	v_mfma_f32_16x16x32_bf16 v[92:95], v[170:173], v[216:219], v[92:95]
	ds_write_b16 v204, v80 offset:62608
	v_cvt_pk_bf16_f32 v80, v82, s0
	v_cndmask_b32_e64 v80, v80, 0, s[16:17]
	ds_write_b16 v204, v80 offset:62752
	v_cvt_pk_bf16_f32 v80, v83, s0
	v_cndmask_b32_e64 v115, v80, 0, s[18:19]
	s_waitcnt lgkmcnt(7)
	v_mfma_f32_16x16x32_bf16 v[80:83], v[88:91], v[224:227], v[92:95]
	ds_write_b16 v204, v115 offset:62896
	v_mfma_f32_16x16x32_bf16 v[96:99], v[84:87], v[166:169], v[162:165]
	v_mfma_f32_16x16x32_bf16 v[76:79], v[84:87], v[174:177], v[76:79]
	s_nop 4
	v_cvt_pk_bf16_f32 v80, v80, s0
	v_cndmask_b32_e64 v80, v80, 0, s[20:21]
	ds_write_b16 v204, v80 offset:62496
	v_cvt_pk_bf16_f32 v80, v81, s0
	v_cndmask_b32_e64 v80, v80, 0, s[22:23]
	s_waitcnt lgkmcnt(8)
	v_mfma_f32_16x16x32_bf16 v[84:87], v[170:173], v[228:231], v[96:99]
	ds_write_b16 v204, v80 offset:62640
	v_cvt_pk_bf16_f32 v80, v82, s0
	v_cndmask_b32_e64 v80, v80, 0, s[24:25]
	s_waitcnt lgkmcnt(7)
	v_mfma_f32_16x16x32_bf16 v[76:79], v[170:173], v[220:223], v[76:79]
	ds_write_b16 v204, v80 offset:62784
	v_cvt_pk_bf16_f32 v80, v83, s0
	v_cndmask_b32_e64 v92, v80, 0, s[26:27]
	v_mfma_f32_16x16x32_bf16 v[80:83], v[88:91], v[232:235], v[84:87]
	ds_write_b16 v204, v92 offset:62928
	s_waitcnt lgkmcnt(8)
	v_mfma_f32_16x16x32_bf16 v[76:79], v[88:91], v[236:239], v[76:79]
	s_nop 4
	v_cvt_pk_bf16_f32 v80, v80, s0
	s_nop 1
	v_cvt_pk_bf16_f32 v76, v76, s0
	v_cndmask_b32_e64 v80, v80, 0, s[28:29]
	v_cndmask_b32_e64 v76, v76, 0, s[38:39]
	ds_write_b16 v204, v80 offset:62528
	v_cvt_pk_bf16_f32 v80, v81, s0
	ds_write_b16 v204, v76 offset:62560
	v_cvt_pk_bf16_f32 v76, v77, s0
	v_cndmask_b32_e64 v80, v80, 0, s[30:31]
	v_cndmask_b32_e64 v76, v76, 0, s[40:41]
	ds_write_b16 v204, v80 offset:62672
	v_cvt_pk_bf16_f32 v80, v82, s0
	ds_write_b16 v204, v76 offset:62704
	v_cvt_pk_bf16_f32 v76, v78, s0
	v_cndmask_b32_e64 v80, v80, 0, s[34:35]
	v_cndmask_b32_e64 v76, v76, 0, s[42:43]
	ds_write_b16 v204, v80 offset:62816
	v_cvt_pk_bf16_f32 v80, v83, s0
	ds_write_b16 v204, v76 offset:62848
	v_cvt_pk_bf16_f32 v76, v79, s0
	v_cndmask_b32_e64 v80, v80, 0, s[36:37]
	v_cndmask_b32_e64 v76, v76, 0, s[44:45]
	ds_write_b16 v204, v80 offset:62960
	ds_write_b16 v204, v76 offset:62992
